# k33 + four more K-fragment LDS reads issued early (ten reads ahead of the prefetch code, spare registers v236-v251), lgkmcnt recounted
# speedup vs baseline: 1.0090x; 1.0016x over previous
; __device__ void phase_attn(const Params& p, unsigned char* smem, int wave) {
;     ...
;     if ((int)blockIdx.x < npairs) { ATT_DECODE(blockIdx.x) ATT_LOAD(); }
;     for (int pr = blockIdx.x; pr < npairs; pr += gridDim.x) {
;         ATT_DECODE(pr)
;         bf16_t* ato = (bf16_t*)(p.ws + (br < 2 ? WS_RA + br * ATO_STRIDE_01 : WS_ATO2));
;         __syncthreads();
;         const int hs = fresh_tid(wave);
; #pragma unroll
;         for (int c_ = 0; c_ < 2; ++c_) { const int e = hs + 512 * c_; *(u32x4*)(Qs + (e >> 3) * ATT_LD + (e & 7) * 8) = qr[c_]; }
; #pragma unroll
;         for (int c_ = 0; c_ < 4; ++c_) { const int e = hs + 512 * c_; *(u32x4*)(Ks + (e >> 3) * ATT_LD + (e & 7) * 8) = kr[c_]; *(u32x4*)(Vs + (e >> 3) * ATT_LD + (e & 7) * 8) = vr[c_]; }
;         __syncthreads();
;         if (pr + (int)gridDim.x < npairs) { ATT_DECODE(pr + gridDim.x) ATT_LOAD(); }
;         const bf16x8 qf0 = *(const bf16x8*)(Qs + (16 * w4 + ql) * ATT_LD + gq * 8), qf1 = *(const bf16x8*)(Qs + (16 * w4 + ql) * ATT_LD + 32 + gq * 8);
.LBB0_722:
	s_waitcnt lgkmcnt(0)
	s_barrier
	v_mbcnt_lo_u32_b32 v12, -1, 0
	v_mbcnt_hi_u32_b32 v12, -1, v12
	s_add_i32 s56, s23, s93
	v_or_b32_e32 v13, s70, v12
	v_lshlrev_b32_e32 v12, 4, v12
	v_and_b32_e32 v12, 0x70, v12
	v_add_u32_e32 v12, 0, v12
	v_lshrrev_b32_e32 v14, 3, v13
	v_mad_u64_u32 v[46:47], s[18:19], v14, s33, v[12:13]
	v_add_u32_e32 v14, 0x200, v13
	v_lshrrev_b32_e32 v14, 3, v14
	v_mad_u64_u32 v[48:49], s[18:19], v14, s33, v[12:13]
	v_add_u32_e32 v14, 0x400, v13
	v_lshrrev_b32_e32 v14, 3, v14
	s_waitcnt vmcnt(18)
	ds_write_b128 v46, v[0:3]
	s_waitcnt vmcnt(17)
	ds_write_b128 v48, v[4:7]
	ds_write_b128 v46, v[16:19] offset:18432
	ds_write_b128 v46, v[20:23] offset:55296
	ds_write_b128 v48, v[8:11] offset:18432
	ds_write_b128 v48, v[24:27] offset:55296
	v_mad_u64_u32 v[46:47], s[18:19], v14, s33, v[12:13]
	v_add_u32_e32 v13, 0x600, v13
	s_cmpk_gt_i32 s56, 0x3bff
	v_lshrrev_b32_e32 v13, 3, v13
	s_cselect_b64 s[46:47], -1, 0
	v_mad_u64_u32 v[12:13], s[18:19], v13, s33, v[12:13]
	s_and_b64 vcc, exec, s[46:47]
	ds_write_b128 v46, v[28:31] offset:18432
	ds_write_b128 v46, v[32:35] offset:55296
	ds_write_b128 v12, v[36:39] offset:18432
	ds_write_b128 v12, v[40:43] offset:55296
	s_waitcnt lgkmcnt(0)
	s_barrier
	ds_read_b128 v[232:235], v140 offset:18432
	ds_read_b128 v[186:189], v140
	ds_read_b128 v[50:53], v140 offset:18496
	ds_read_b128 v[190:193], v140 offset:64
	ds_read_b128 v[54:57], v140 offset:20736
	ds_read_b128 v[58:61], v140 offset:20800
	ds_read_b128 v[236:239], v140 offset:23040
	ds_read_b128 v[240:243], v140 offset:23104
	ds_read_b128 v[244:247], v140 offset:25344
	ds_read_b128 v[248:251], v140 offset:25408
	s_cbranch_vccnz .LBB0_732
	s_mul_hi_i32 s18, s56, 0x66666667
	s_lshr_b32 s19, s18, 31
	s_ashr_i32 s18, s18, 8
	s_add_i32 s18, s18, s19
	s_mul_i32 s19, s18, 0xfffffd80
	s_mul_i32 s27, s18, 0xfffec000
	s_add_i32 s28, s49, s48
	s_add_i32 s19, s56, s19
	s_add_i32 s28, s28, s27
	s_and_b32 s26, s18, -8
	s_and_b32 s27, s28, 0xfffff800
	s_and_b32 s28, s19, 15
	s_add_i32 s29, s19, 0xfffffe00
	s_cmp_eq_u32 s26, 8
	s_cselect_b32 s26, 2, 4
	s_cselect_b32 s30, 3, 15
	s_cmp_lt_u32 s18, 8
	s_cselect_b32 s26, 0, s26
	s_cselect_b32 s30, 0, s30
	s_cmpk_lt_i32 s19, 0x200
	s_cselect_b32 s19, s28, s29
	s_cselect_b32 s27, s27, 0x10000
	s_cselect_b32 s28, s50, 0x4000
	s_and_b32 s29, s30, s19
	s_lshr_b32 s19, s19, s26
	v_mbcnt_lo_u32_b32 v0, -1, 0
	v_mbcnt_hi_u32_b32 v0, -1, v0
	s_lshl_b32 s18, s18, 6
	v_or_b32_e32 v13, s70, v0
	s_lshl_b32 s19, s19, 7
	s_and_b32 s18, s18, 0x1c0
	v_lshlrev_b32_e32 v0, 3, v0
	v_ashrrev_i32_e32 v8, 3, v13
	v_add_u32_e32 v2, 0x200, v13
	v_and_or_b32 v12, v0, 56, s18
	v_add_u32_e32 v0, s19, v8
	v_ashrrev_i32_e32 v24, 3, v2
	s_or_b32 s27, s29, s27
	v_lshlrev_b32_e32 v0, s26, v0
	v_add_u32_e32 v2, s19, v24
	v_add_u32_e32 v0, s27, v0
	v_lshlrev_b32_e32 v2, s26, v2
	v_mul_lo_u32 v0, v0, s3
	v_add_u32_e32 v2, s27, v2
	v_or_b32_e32 v14, v0, v12
	v_mul_lo_u32 v2, v2, s3
	v_lshl_add_u64 v[0:1], v[14:15], 1, s[38:39]
	v_or_b32_e32 v14, v2, v12
	v_lshl_add_u64 v[4:5], v[14:15], 1, s[38:39]
	global_load_dwordx4 v[0:3], v[0:1], off
	s_nop 0
	global_load_dwordx4 v[4:7], v[4:5], off
	s_sub_i32 s29, s19, 64
	s_lshr_b32 s28, s28, s26
	v_add_u32_e32 v14, s29, v8
	v_mov_b32_e32 v10, v44
	v_mov_b32_e32 v11, v44
	v_cmp_lt_i32_e32 vcc, -1, v14
	v_cmp_gt_i32_e64 s[18:19], s28, v14
	v_mov_b32_e32 v8, 0
	v_mov_b32_e32 v9, v44
	v_mov_b64_e32 v[18:19], v[10:11]
	v_mov_b64_e32 v[22:23], v[10:11]
	s_and_b64 s[30:31], vcc, s[18:19]
	v_mov_b64_e32 v[16:17], v[8:9]
	v_mov_b64_e32 v[20:21], v[8:9]
	s_and_saveexec_b64 s[18:19], s[30:31]
	s_cbranch_execz .LBB0_725
	v_lshlrev_b32_e32 v14, s26, v14
	v_add_u32_e32 v14, s27, v14
	v_mul_lo_u32 v14, v14, s3
	v_or_b32_e32 v14, v14, v12
	v_lshl_add_u64 v[20:21], v[14:15], 1, s[38:39]
	global_load_dwordx4 v[16:19], v[20:21], off offset:1024
	s_nop 0
	global_load_dwordx4 v[20:23], v[20:21], off offset:2048

; __device__ void phase_attn(const Params& p, unsigned char* smem, int wave) {
;     ...
;         const bf16x8 qf0 = *(const bf16x8*)(Qs + (16 * w4 + ql) * ATT_LD + gq * 8), qf1 = *(const bf16x8*)(Qs + (16 * w4 + ql) * ATT_LD + 32 + gq * 8);
;         f32x4 sc[10];
; #pragma unroll
;         for (int kt = 0; kt < 9; ++kt) { const bf16_t* kr = Ks + (16 * w4 + 16 * kt + ql) * ATT_LD + gq * 8;
;             f32x4 a = (f32x4){0.f, 0.f, 0.f, 0.f};
;             a = __builtin_amdgcn_mfma_f32_16x16x32_bf16(*(const bf16x8*)kr, qf0, a, 0, 0, 0);
;             a = __builtin_amdgcn_mfma_f32_16x16x32_bf16(*(const bf16x8*)(kr + 32), qf1, a, 0, 0, 0);
;             sc[kt] = a; if (kt % 3 == 2) __builtin_amdgcn_sched_barrier(0); }
;         const float slope = exp2f(-(float)(h + 1)) * (float)d * 1.4426950408889634f;
;         const int qi = i0 + 16 * w4 + ql;
;         float mx = -1e30f;
; #pragma unroll
;         for (int kt = 0; kt < 9; ++kt)
; #pragma unroll
;             for (int j = 0; j < 4; ++j) { const int rel = 16 * kt + 4 * gq + j - 64 - ql; const int jk = qi + rel;
;                 const bool relok = (kt == 0) ? (rel >= -64) : ((kt == 8) ? (rel <= 64) : true);
;                 const bool ok = relok && ((unsigned)jk < (unsigned)Ls);
;                 const float v = ok ? sc[kt][j] * 0.18033688011112042f - slope * fabsf((float)rel) : -1e30f;
;                 sc[kt][j] = v; mx = fmaxf(mx, v); }
.LBB0_732:
	v_readlane_b32 s28, v253, 8
	v_readlane_b32 s30, v253, 10
	v_readlane_b32 s31, v253, 11
	s_add_u32 s59, s30, s20
	s_mul_i32 s18, s22, 0xfffffd80
	s_waitcnt lgkmcnt(8)
	v_mfma_f32_16x16x32_bf16 v[46:49], v[232:235], v[186:189], 0
	s_mul_i32 s19, s22, 0xfffec000
	s_addc_u32 s60, s31, s21
	s_add_i32 s18, s23, s18
	s_waitcnt lgkmcnt(6)
	v_mfma_f32_16x16x32_bf16 v[194:197], v[50:53], v[190:193], v[46:49]
	s_add_i32 s19, s48, s19
	s_and_b32 s57, s22, 7
	s_and_b32 s19, s19, 0xfffff800
	s_waitcnt lgkmcnt(5)
	v_mfma_f32_16x16x32_bf16 v[50:53], v[54:57], v[186:189], 0
	s_and_b32 s20, s18, 15
	s_add_i32 s21, s18, 0xfffffe00
	s_cmpk_lt_i32 s18, 0x200
	s_cselect_b32 s18, s20, s21
	s_cselect_b32 s20, s50, 0x4000
	s_cselect_b32 s61, s19, 0x10000
	s_cmp_eq_u32 s42, 1
	s_cselect_b32 s19, 4, 16
	s_cselect_b32 s21, 2, 4
	s_cmp_lt_u32 s22, 8
	s_waitcnt lgkmcnt(3)
	v_mfma_f32_16x16x32_bf16 v[46:49], v[236:239], v[186:189], 0
	s_cselect_b32 s22, 1, s19
	s_cselect_b32 s58, 0, s21
	s_add_i32 s19, s22, -1
	s_lshr_b32 s63, s20, s58
	s_and_b32 s62, s19, s18
	s_lshr_b32 s20, s18, s58
	v_readlane_b32 s29, v253, 9
	v_mfma_f32_16x16x32_bf16 v[198:201], v[58:61], v[190:193], v[50:53]
	s_waitcnt lgkmcnt(2)
	v_mfma_f32_16x16x32_bf16 v[202:205], v[240:243], v[190:193], v[46:49]
	s_nop 2
	ds_read_b128 v[54:57], v140 offset:27648
	ds_read_b128 v[58:61], v140 offset:27712
	s_waitcnt lgkmcnt(3)
	v_mfma_f32_16x16x32_bf16 v[46:49], v[244:247], v[186:189], 0
	s_waitcnt lgkmcnt(2)
	v_mfma_f32_16x16x32_bf16 v[206:209], v[248:251], v[190:193], v[46:49]
	ds_read_b128 v[50:53], v140 offset:30016
	s_nop 4
	ds_read_b128 v[46:49], v140 offset:29952
	s_waitcnt lgkmcnt(3)
	v_mfma_f32_16x16x32_bf16 v[54:57], v[54:57], v[186:189], 0
	s_waitcnt lgkmcnt(0)
	v_mfma_f32_16x16x32_bf16 v[46:49], v[46:49], v[186:189], 0
	v_mfma_f32_16x16x32_bf16 v[62:65], v[58:61], v[190:193], v[54:57]
	v_mfma_f32_16x16x32_bf16 v[58:61], v[50:53], v[190:193], v[46:49]
	s_nop 5
	ds_read_b128 v[46:49], v140 offset:32256
	ds_read_b128 v[50:53], v140 offset:32320
	ds_read_b128 v[54:57], v140 offset:34560
	ds_read_b128 v[210:213], v140 offset:34624
	s_waitcnt lgkmcnt(3)
	v_mfma_f32_16x16x32_bf16 v[46:49], v[46:49], v[186:189], 0
	s_waitcnt lgkmcnt(1)
	v_mfma_f32_16x16x32_bf16 v[214:217], v[54:57], v[186:189], 0
	v_mfma_f32_16x16x32_bf16 v[54:57], v[50:53], v[190:193], v[46:49]
	s_nop 4
	ds_read_b128 v[46:49], v140 offset:36864
	s_waitcnt lgkmcnt(1)
	v_mfma_f32_16x16x32_bf16 v[50:53], v[210:213], v[190:193], v[214:217]
	ds_read_b128 v[210:213], v140 offset:36928
	s_waitcnt lgkmcnt(1)
	v_mfma_f32_16x16x32_bf16 v[46:49], v[46:49], v[186:189], 0
	s_waitcnt lgkmcnt(0)
	v_mfma_f32_16x16x32_bf16 v[46:49], v[210:213], v[190:193], v[46:49]
	s_add_i32 s18, s57, 1
	v_cvt_f32_ubyte0_e32 v12, s18
	v_cmp_lt_f32_e32 vcc, s51, v12
	s_and_b64 s[18:19], vcc, exec
	s_cselect_b32 s18, 0xffffffc0, 0
	v_cndmask_b32_e32 v13, 0, v181, vcc
	v_sub_f32_e32 v12, v13, v12
	v_exp_f32_e32 v12, v12
	v_lshl_add_u32 v139, s20, 7, v67
	v_cvt_f32_ubyte0_e32 v13, s22
	v_or_b32_e32 v45, v139, v66
	v_ldexp_f32 v12, v12, s18
	v_mul_f32_e32 v13, v12, v13
	v_add_u32_e32 v12, v45, v143
	v_cmp_gt_u32_e64 s[26:27], s63, v12
	v_add_u32_e32 v12, v45, v144
	v_cmp_gt_u32_e64 s[28:29], s63, v12
	v_add_u32_e32 v12, v45, v145
	v_cmp_gt_u32_e64 s[30:31], s63, v12
	v_add_u32_e32 v12, v45, v146
	v_cmp_gt_u32_e64 s[34:35], s63, v12
	v_add_u32_e32 v12, v45, v174
	v_cmp_gt_u32_e64 s[22:23], s63, v12
	v_add_u32_e32 v12, v45, v175
	v_cmp_gt_u32_e64 s[20:21], s63, v12
	v_add_u32_e32 v12, v45, v176
	v_cmp_gt_u32_e32 vcc, s63, v12
	v_add_u32_e32 v12, v45, v177
	v_cmp_gt_u32_e64 s[18:19], s63, v12
	v_mov_b32_e32 v12, v49
	v_pk_mul_f32 v[12:13], v[12:13], s[44:45]
	v_mov_b32_e32 v186, v194
	v_mov_b32_e32 v187, v13
	v_pk_mul_f32 v[186:187], v[68:69], v[186:187]
	s_and_b64 s[26:27], s[24:25], s[26:27]
	v_sub_f32_e32 v49, v186, v187
	v_mov_b32_e32 v186, v195
	v_mov_b32_e32 v187, v13
	v_pk_mul_f32 v[186:187], v[70:71], v[186:187]
	v_cndmask_b32_e64 v194, v182, v49, s[26:27]
	v_sub_f32_e32 v49, v186, v187
	v_mov_b32_e32 v186, v196
	v_mov_b32_e32 v187, v13
	s_and_b64 s[26:27], s[4:5], s[28:29]
	v_pk_mul_f32 v[186:187], v[72:73], v[186:187]
	v_cndmask_b32_e64 v195, v182, v49, s[26:27]
	v_sub_f32_e32 v186, v186, v187
	s_and_b64 s[26:27], s[6:7], s[30:31]
	v_cndmask_b32_e64 v196, v182, v186, s[26:27]
	v_mov_b32_e32 v186, v197
	v_mov_b32_e32 v187, v13
	v_pk_mul_f32 v[186:187], v[74:75], v[186:187]
	s_and_b64 s[26:27], s[8:9], s[34:35]
	v_sub_f32_e32 v186, v186, v187
	v_cndmask_b32_e64 v197, v182, v186, s[26:27]
	v_mov_b32_e32 v186, v198
	v_mov_b32_e32 v187, v13
	v_add_u32_e32 v14, v45, v147
	v_pk_mul_f32 v[186:187], v[76:77], v[186:187]
	v_cmp_gt_u32_e64 s[26:27], s63, v14
	v_sub_f32_e32 v186, v186, v187
	v_mov_b32_e32 v187, v13
	v_cndmask_b32_e64 v14, v182, v186, s[26:27]
	v_mov_b32_e32 v186, v199
	v_add_u32_e32 v188, v45, v148
	v_pk_mul_f32 v[186:187], v[78:79], v[186:187]
	v_cmp_gt_u32_e64 s[26:27], s63, v188
	v_sub_f32_e32 v186, v186, v187
	v_mov_b32_e32 v187, v13
	v_cndmask_b32_e64 v188, v182, v186, s[26:27]
	v_mov_b32_e32 v186, v200
	v_add_u32_e32 v189, v45, v149
	v_pk_mul_f32 v[186:187], v[80:81], v[186:187]
	v_cmp_gt_u32_e64 s[26:27], s63, v189
	v_sub_f32_e32 v186, v186, v187
	v_mov_b32_e32 v187, v13
	v_cndmask_b32_e64 v189, v182, v186, s[26:27]
	v_mov_b32_e32 v186, v201
	v_add_u32_e32 v190, v45, v150
	v_pk_mul_f32 v[186:187], v[82:83], v[186:187]
	v_cmp_gt_u32_e64 s[26:27], s63, v190
	v_sub_f32_e32 v186, v186, v187
	v_mov_b32_e32 v187, v13
	v_cndmask_b32_e64 v190, v182, v186, s[26:27]
	v_mov_b32_e32 v186, v202
	v_add_u32_e32 v191, v45, v151
	v_pk_mul_f32 v[186:187], v[84:85], v[186:187]
; __device__ void phase_attn(const Params& p, unsigned char* smem, int wave) {
;     ...
; #pragma unroll
;         for (int kt = 0; kt < 9; ++kt)
; #pragma unroll
;             for (int j = 0; j < 4; ++j) { const int rel = 16 * kt + 4 * gq + j - 64 - ql; const int jk = qi + rel;
;                 const bool relok = (kt == 0) ? (rel >= -64) : ((kt == 8) ? (rel <= 64) : true);
;                 const bool ok = relok && ((unsigned)jk < (unsigned)Ls);
;                 const float v = ok ? sc[kt][j] * 0.18033688011112042f - slope * fabsf((float)rel) : -1e30f;
;                 sc[kt][j] = v; mx = fmaxf(mx, v); }
	v_cmp_gt_u32_e64 s[26:27], s63, v191
	v_sub_f32_e32 v186, v186, v187
	v_mov_b32_e32 v187, v13
	v_cndmask_b32_e64 v191, v182, v186, s[26:27]
	v_mov_b32_e32 v186, v203
	v_add_u32_e32 v192, v45, v152
	v_pk_mul_f32 v[186:187], v[86:87], v[186:187]
	v_cmp_gt_u32_e64 s[26:27], s63, v192
	v_sub_f32_e32 v186, v186, v187
	v_mov_b32_e32 v187, v13
	v_cndmask_b32_e64 v192, v182, v186, s[26:27]
	v_mov_b32_e32 v186, v204
	v_add_u32_e32 v193, v45, v153
	v_pk_mul_f32 v[186:187], v[88:89], v[186:187]
	v_cmp_gt_u32_e64 s[26:27], s63, v193
	v_sub_f32_e32 v186, v186, v187
	v_mov_b32_e32 v187, v13
	v_cndmask_b32_e64 v193, v182, v186, s[26:27]
	v_mov_b32_e32 v186, v205
	v_add_u32_e32 v210, v45, v154
	v_pk_mul_f32 v[186:187], v[90:91], v[186:187]
	v_cmp_gt_u32_e64 s[26:27], s63, v210
	v_sub_f32_e32 v186, v186, v187
	v_mov_b32_e32 v187, v13
	v_cndmask_b32_e64 v198, v182, v186, s[26:27]
	v_mov_b32_e32 v186, v206
	v_add_u32_e32 v211, v45, v155
	v_pk_mul_f32 v[186:187], v[92:93], v[186:187]
	v_cmp_gt_u32_e64 s[26:27], s63, v211
	v_sub_f32_e32 v186, v186, v187
	v_mov_b32_e32 v187, v13
	v_cndmask_b32_e64 v199, v182, v186, s[26:27]
	v_mov_b32_e32 v186, v207
	v_add_u32_e32 v212, v45, v156
	v_pk_mul_f32 v[186:187], v[94:95], v[186:187]
	v_cmp_gt_u32_e64 s[26:27], s63, v212
	v_sub_f32_e32 v186, v186, v187
	v_mov_b32_e32 v187, v13
	v_cndmask_b32_e64 v200, v182, v186, s[26:27]
	v_mov_b32_e32 v186, v208
	v_add_u32_e32 v213, v45, v157
	v_pk_mul_f32 v[186:187], v[96:97], v[186:187]
	v_cmp_gt_u32_e64 s[26:27], s63, v213
	v_sub_f32_e32 v186, v186, v187
	v_mov_b32_e32 v187, v13
	v_cndmask_b32_e64 v201, v182, v186, s[26:27]
	v_mov_b32_e32 v186, v209
	v_add_u32_e32 v214, v45, v158
	v_pk_mul_f32 v[186:187], v[98:99], v[186:187]
	v_cmp_gt_u32_e64 s[26:27], s63, v214
	v_sub_f32_e32 v186, v186, v187
	v_mov_b32_e32 v187, v13
	v_cndmask_b32_e64 v202, v182, v186, s[26:27]
	v_mov_b32_e32 v186, v62
	v_add_u32_e32 v215, v45, v142
	v_pk_mul_f32 v[186:187], v[100:101], v[186:187]
	v_cmp_gt_u32_e64 s[26:27], s63, v215
	v_sub_f32_e32 v62, v186, v187
	v_add_u32_e32 v216, v45, v159
	v_cndmask_b32_e64 v186, v182, v62, s[26:27]
	v_mov_b32_e32 v62, v63
	v_mov_b32_e32 v63, v13
	v_pk_mul_f32 v[62:63], v[102:103], v[62:63]
	v_cmp_gt_u32_e64 s[26:27], s63, v216
	v_sub_f32_e32 v62, v62, v63
	v_mov_b32_e32 v63, v13
	v_cndmask_b32_e64 v187, v182, v62, s[26:27]
	v_mov_b32_e32 v62, v64
	v_add_u32_e32 v217, v45, v160
	v_pk_mul_f32 v[62:63], v[104:105], v[62:63]
	v_cmp_gt_u32_e64 s[26:27], s63, v217
	v_sub_f32_e32 v62, v62, v63
	v_mov_b32_e32 v63, v13
	v_cndmask_b32_e64 v64, v182, v62, s[26:27]
	v_mov_b32_e32 v62, v65
	v_add_u32_e32 v218, v45, v161
	v_pk_mul_f32 v[62:63], v[106:107], v[62:63]
	v_cmp_gt_u32_e64 s[26:27], s63, v218
	v_sub_f32_e32 v62, v62, v63
	v_mov_b32_e32 v63, v13
	v_cndmask_b32_e64 v65, v182, v62, s[26:27]
	v_mov_b32_e32 v62, v58
	v_add_u32_e32 v219, v45, v162
	v_pk_mul_f32 v[62:63], v[62:63], v[108:109]
	v_cmp_gt_u32_e64 s[26:27], s63, v219
	v_sub_f32_e32 v58, v62, v63
	v_add_u32_e32 v220, v45, v163
	v_cndmask_b32_e64 v62, v182, v58, s[26:27]
	v_mov_b32_e32 v58, v59
	v_mov_b32_e32 v59, v13
	v_pk_mul_f32 v[58:59], v[58:59], v[110:111]
	v_cmp_gt_u32_e64 s[26:27], s63, v220
	v_sub_f32_e32 v58, v58, v59
	v_mov_b32_e32 v59, v13
	v_cndmask_b32_e64 v63, v182, v58, s[26:27]
	v_mov_b32_e32 v58, v60
	v_add_u32_e32 v221, v45, v164
	v_pk_mul_f32 v[58:59], v[58:59], v[112:113]
	v_cmp_gt_u32_e64 s[26:27], s63, v221
	v_sub_f32_e32 v58, v58, v59
	v_mov_b32_e32 v59, v13
	v_cndmask_b32_e64 v60, v182, v58, s[26:27]
	v_mov_b32_e32 v58, v61
	v_add_u32_e32 v222, v45, v165
	v_pk_mul_f32 v[58:59], v[58:59], v[114:115]
	v_cmp_gt_u32_e64 s[26:27], s63, v222
	v_sub_f32_e32 v58, v58, v59
	v_mov_b32_e32 v59, v13
	v_cndmask_b32_e64 v61, v182, v58, s[26:27]
	v_mov_b32_e32 v58, v54
	v_add_u32_e32 v223, v45, v166
	v_pk_mul_f32 v[58:59], v[58:59], v[116:117]
	v_cmp_gt_u32_e64 s[26:27], s63, v223
	v_sub_f32_e32 v54, v58, v59
	v_add_u32_e32 v224, v45, v167
	v_cndmask_b32_e64 v58, v182, v54, s[26:27]
	v_mov_b32_e32 v54, v55
	v_mov_b32_e32 v55, v13
	v_pk_mul_f32 v[54:55], v[54:55], v[118:119]
	v_cmp_gt_u32_e64 s[26:27], s63, v224
	v_sub_f32_e32 v54, v54, v55
	v_mov_b32_e32 v55, v13
	v_cndmask_b32_e64 v59, v182, v54, s[26:27]
	v_mov_b32_e32 v54, v56
	v_add_u32_e32 v225, v45, v168
	v_pk_mul_f32 v[54:55], v[54:55], v[120:121]
	v_cmp_gt_u32_e64 s[26:27], s63, v225
	v_sub_f32_e32 v54, v54, v55
	v_mov_b32_e32 v55, v13
	v_cndmask_b32_e64 v56, v182, v54, s[26:27]
	v_mov_b32_e32 v54, v57
	v_add_u32_e32 v226, v45, v169
	v_pk_mul_f32 v[54:55], v[54:55], v[122:123]
	v_cmp_gt_u32_e64 s[26:27], s63, v226
	v_sub_f32_e32 v54, v54, v55
	v_mov_b32_e32 v55, v13
	v_cndmask_b32_e64 v57, v182, v54, s[26:27]
	v_mov_b32_e32 v54, v50
	v_add_u32_e32 v227, v45, v170
	v_pk_mul_f32 v[54:55], v[54:55], v[124:125]
	v_cmp_gt_u32_e64 s[26:27], s63, v227
	v_sub_f32_e32 v50, v54, v55
	v_max3_f32 v49, v194, s52, v195
	v_cndmask_b32_e64 v54, v182, v50, s[26:27]
	v_mov_b32_e32 v50, v51
	v_mov_b32_e32 v51, v13
	v_add_u32_e32 v228, v45, v171
	v_max3_f32 v49, v49, v196, v197
	v_pk_mul_f32 v[50:51], v[50:51], v[126:127]
	v_max3_f32 v49, v49, v14, v188
	v_sub_f32_e32 v50, v50, v51
	v_cmp_gt_u32_e64 s[26:27], s63, v228
	v_max3_f32 v49, v49, v189, v190
	v_mov_b32_e32 v51, v13
	v_cndmask_b32_e64 v55, v182, v50, s[26:27]
	v_mov_b32_e32 v50, v52
	v_add_u32_e32 v229, v45, v172
	v_max3_f32 v49, v49, v191, v192
	v_pk_mul_f32 v[50:51], v[50:51], v[128:129]
	v_max3_f32 v49, v49, v193, v198
	v_sub_f32_e32 v50, v50, v51
	v_cmp_gt_u32_e64 s[26:27], s63, v229
	v_max3_f32 v49, v49, v199, v200
	v_mov_b32_e32 v51, v13
	v_cndmask_b32_e64 v52, v182, v50, s[26:27]
	v_mov_b32_e32 v50, v53
; __device__ __forceinline__ unsigned cvtpk(float lo, float hi) { const f32v2_t v = {lo, hi}; const bf16v2_t b = __builtin_convertvector(v, bf16v2_t); return __builtin_bit_cast(unsigned, b); }
; __device__ __forceinline__ v4i16_t lds_tr16(const bf16_t* p) { return __builtin_amdgcn_ds_read_tr16_b64_v4i16((LAS v4i16_t*)p); }
; __device__ void phase_attn(const Params& p, unsigned char* smem, int wave) {
;     ...
;         mx = fmaxf(mx, __shfl_xor(mx, 16)); mx = fmaxf(mx, __shfl_xor(mx, 32));
;         float den = 0.f;
; #pragma unroll
;         for (int kt = 0; kt < 9; ++kt)
; #pragma unroll
;             for (int j = 0; j < 4; ++j) { const float pv = __builtin_amdgcn_exp2f(sc[kt][j] - mx); sc[kt][j] = pv; den += pv; }
;         sc[9] = (f32x4){0.f, 0.f, 0.f, 0.f};
;         den += __shfl_xor(den, 16); den += __shfl_xor(den, 32);
;         f32x4 oacc[4];
; #pragma unroll
;         for (int et = 0; et < 4; ++et) oacc[et] = (f32x4){0.f, 0.f, 0.f, 0.f};
; #pragma unroll
;         for (int ks = 0; ks < 5; ++ks) {
;             u32x4 pu; pu.x = cvtpk(sc[2 * ks][0], sc[2 * ks][1]); pu.y = cvtpk(sc[2 * ks][2], sc[2 * ks][3]); pu.z = cvtpk(sc[2 * ks + 1][0], sc[2 * ks + 1][1]); pu.w = cvtpk(sc[2 * ks + 1][2], sc[2 * ks + 1][3]);
;             const bf16x8 pf = __builtin_bit_cast(bf16x8, pu);
;             const bf16_t* vrow = Vs + (16 * w4 + 32 * ks + 4 * gq + (ql >> 2)) * ATT_LD + 4 * (ql & 3);
; #pragma unroll
;             for (int et = 0; et < 4; ++et) {
;                 const v4i16_t t0 = lds_tr16(vrow + 16 * et);
;                 v4i16_t t1 = (v4i16_t){0, 0, 0, 0};
;                 if (ks < 4) t1 = lds_tr16(vrow + 16 * ATT_LD + 16 * et);
;                 const bf16x8 vf = __builtin_shufflevector(t0, t1, 0, 1, 2, 3, 4, 5, 6, 7);
;                 oacc[et] = __builtin_amdgcn_mfma_f32_16x16x32_bf16(pf, vf, oacc[et], 0, 0, 0); }
	v_add_u32_e32 v230, v45, v173
	v_max3_f32 v49, v49, v201, v202
	v_pk_mul_f32 v[50:51], v[50:51], v[130:131]
	v_max3_f32 v49, v49, v186, v187
	v_sub_f32_e32 v50, v50, v51
	v_cmp_gt_u32_e64 s[26:27], s63, v230
	v_max3_f32 v49, v49, v64, v65
	v_mov_b32_e32 v51, v13
	v_cndmask_b32_e64 v53, v182, v50, s[26:27]
	v_mov_b32_e32 v50, v46
	v_max3_f32 v49, v49, v62, v63
	v_pk_mul_f32 v[50:51], v[50:51], v[132:133]
	v_max3_f32 v49, v49, v60, v61
	v_sub_f32_e32 v46, v50, v51
	s_and_b64 s[22:23], s[10:11], s[22:23]
	v_max3_f32 v49, v49, v58, v59
	v_cndmask_b32_e64 v50, v182, v46, s[22:23]
	v_mov_b32_e32 v46, v47
	v_mov_b32_e32 v47, v13
	v_max3_f32 v49, v49, v56, v57
	v_pk_mul_f32 v[46:47], v[46:47], v[134:135]
	v_max3_f32 v49, v49, v54, v55
	v_sub_f32_e32 v46, v46, v47
	s_and_b64 s[20:21], s[12:13], s[20:21]
	v_max3_f32 v49, v49, v52, v53
	v_cndmask_b32_e64 v51, v182, v46, s[20:21]
	v_max3_f32 v203, v49, v50, v51
	v_mov_b32_e32 v49, v13
	v_pk_mul_f32 v[46:47], v[48:49], v[136:137]
	s_and_b64 vcc, s[14:15], vcc
	v_sub_f32_e32 v46, v46, v47
	v_and_b32_e32 v206, 64, v183
	v_cndmask_b32_e32 v47, v182, v46, vcc
	v_fma_f32 v12, -v13, v178, v12
	s_and_b64 vcc, s[16:17], s[18:19]
	v_xor_b32_e32 v46, 16, v183
	v_add_u32_e32 v48, 64, v206
	v_cndmask_b32_e32 v12, v182, v12, vcc
	v_cmp_lt_i32_e32 vcc, v46, v48
	v_max3_f32 v13, v203, v47, v12
	s_nop 0
	v_cndmask_b32_e32 v46, v183, v46, vcc
	v_lshlrev_b32_e32 v203, 2, v46
	ds_bpermute_b32 v46, v203, v13
	s_waitcnt lgkmcnt(0)
	v_max_f32_e32 v46, v46, v46
	v_max_f32_e32 v13, v13, v46
	v_xor_b32_e32 v46, 32, v183
	v_cmp_lt_i32_e32 vcc, v46, v48
	s_nop 1
	v_cndmask_b32_e32 v46, v183, v46, vcc
	v_lshlrev_b32_e32 v204, 2, v46
	ds_bpermute_b32 v46, v204, v13
	s_waitcnt lgkmcnt(0)
	v_max_f32_e32 v46, v46, v46
	v_max_f32_e32 v46, v13, v46
	v_sub_f32_e32 v13, v194, v46
	v_exp_f32_e32 v13, v13
	v_sub_f32_e32 v49, v195, v46
	v_exp_f32_e32 v49, v49
	v_sub_f32_e32 v194, v196, v46
	v_exp_f32_e32 v194, v194
	v_sub_f32_e32 v195, v197, v46
	v_exp_f32_e32 v195, v195
	v_sub_f32_e32 v14, v14, v46
	v_add_f32_e32 v48, 0, v13
	v_exp_f32_e32 v14, v14
	v_sub_f32_e32 v188, v188, v46
	v_add_f32_e32 v48, v49, v48
	v_exp_f32_e32 v188, v188
	v_sub_f32_e32 v189, v189, v46
	v_add_f32_e32 v48, v194, v48
	v_exp_f32_e32 v189, v189
	v_sub_f32_e32 v190, v190, v46
	v_add_f32_e32 v48, v195, v48
	v_exp_f32_e32 v190, v190
	v_sub_f32_e32 v191, v191, v46
	v_add_f32_e32 v48, v14, v48
	v_exp_f32_e32 v191, v191
	v_sub_f32_e32 v192, v192, v46
	v_add_f32_e32 v48, v188, v48
	v_exp_f32_e32 v192, v192
	v_sub_f32_e32 v193, v193, v46
	v_add_f32_e32 v48, v189, v48
	v_exp_f32_e32 v193, v193
	v_sub_f32_e32 v196, v198, v46
	v_add_f32_e32 v48, v190, v48
	v_exp_f32_e32 v196, v196
	v_sub_f32_e32 v197, v199, v46
	v_add_f32_e32 v48, v191, v48
	v_exp_f32_e32 v197, v197
	v_sub_f32_e32 v198, v200, v46
	v_add_f32_e32 v48, v192, v48
	v_exp_f32_e32 v198, v198
	v_sub_f32_e32 v199, v201, v46
	v_add_f32_e32 v48, v193, v48
	v_exp_f32_e32 v199, v199
	v_sub_f32_e32 v200, v202, v46
	v_add_f32_e32 v48, v196, v48
	v_exp_f32_e32 v200, v200
	v_sub_f32_e32 v186, v186, v46
	v_add_f32_e32 v48, v197, v48
	v_exp_f32_e32 v207, v186
	v_sub_f32_e32 v186, v187, v46
	v_add_f32_e32 v48, v198, v48
	v_exp_f32_e32 v208, v186
	v_sub_f32_e32 v64, v64, v46
	v_add_f32_e32 v48, v199, v48
	v_exp_f32_e32 v64, v64
	v_sub_f32_e32 v65, v65, v46
	v_add_f32_e32 v48, v200, v48
	v_exp_f32_e32 v65, v65
	v_sub_f32_e32 v62, v62, v46
	v_add_f32_e32 v48, v207, v48
	v_exp_f32_e32 v209, v62
	v_sub_f32_e32 v62, v63, v46
	v_add_f32_e32 v48, v208, v48
	v_exp_f32_e32 v210, v62
	v_sub_f32_e32 v60, v60, v46
	v_add_f32_e32 v48, v64, v48
	v_exp_f32_e32 v211, v60
	v_sub_f32_e32 v60, v61, v46
	v_add_f32_e32 v48, v65, v48
	v_exp_f32_e32 v212, v60
	v_sub_f32_e32 v58, v58, v46
	v_add_f32_e32 v48, v209, v48
	v_exp_f32_e32 v213, v58
	v_sub_f32_e32 v58, v59, v46
	v_add_f32_e32 v48, v210, v48
	v_exp_f32_e32 v214, v58
	v_sub_f32_e32 v56, v56, v46
	v_add_f32_e32 v48, v211, v48
	v_exp_f32_e32 v215, v56
	v_sub_f32_e32 v56, v57, v46
	v_add_f32_e32 v48, v212, v48
	v_exp_f32_e32 v216, v56
	v_sub_f32_e32 v54, v54, v46
	v_add_f32_e32 v48, v213, v48
	v_exp_f32_e32 v217, v54
	v_sub_f32_e32 v54, v55, v46
	v_add_f32_e32 v48, v214, v48
	v_exp_f32_e32 v218, v54
	v_sub_f32_e32 v52, v52, v46
	v_add_f32_e32 v48, v215, v48
	v_exp_f32_e32 v219, v52
	v_sub_f32_e32 v52, v53, v46
	v_add_f32_e32 v48, v216, v48
	v_exp_f32_e32 v220, v52
	v_sub_f32_e32 v50, v50, v46
	v_add_f32_e32 v48, v217, v48
	v_exp_f32_e32 v221, v50
	v_add_f32_e32 v48, v218, v48
	v_add_f32_e32 v48, v219, v48
	v_add_f32_e32 v48, v220, v48
	v_add_f32_e32 v201, v221, v48
	v_sub_f32_e32 v48, v51, v46
	v_exp_f32_e32 v222, v48
	v_sub_f32_e32 v47, v47, v46
	v_cvt_pk_bf16_f32 v48, v13, v49
	v_exp_f32_e32 v13, v47
	v_sub_f32_e32 v12, v12, v46
	v_cvt_pk_bf16_f32 v50, v14, v188
	v_exp_f32_e32 v14, v12
	v_add_f32_e32 v12, v222, v201
	v_add_f32_e32 v12, v13, v12
	v_cvt_pk_bf16_f32 v49, v194, v195
	v_add_f32_e32 v12, v14, v12
	ds_bpermute_b32 v47, v203, v12
	v_cvt_pk_bf16_f32 v51, v189, v190
	ds_read_b64_tr_b16 v[54:55], v179 offset:57600
	ds_read_b64_tr_b16 v[52:53], v179 offset:55296
	ds_read_b64_tr_b16 v[56:57], v179 offset:55328
	ds_read_b64_tr_b16 v[60:61], v179 offset:55360
	ds_read_b64_tr_b16 v[186:187], v179 offset:55392
	ds_read_b64_tr_b16 v[58:59], v179 offset:57632
	ds_read_b64_tr_b16 v[62:63], v179 offset:57664
	ds_read_b64_tr_b16 v[188:189], v179 offset:57696
	s_waitcnt lgkmcnt(6)
	v_mfma_f32_16x16x32_bf16 v[52:55], v[48:51], v[52:55], 0
	v_add_f32_e32 v47, v12, v47
	ds_bpermute_b32 v223, v204, v47
	s_waitcnt lgkmcnt(3)
	v_mfma_f32_16x16x32_bf16 v[56:59], v[48:51], v[56:59], 0
	s_waitcnt lgkmcnt(2)
; __device__ __forceinline__ unsigned cvtpk(float lo, float hi) { const f32v2_t v = {lo, hi}; const bf16v2_t b = __builtin_convertvector(v, bf16v2_t); return __builtin_bit_cast(unsigned, b); }
; __device__ __forceinline__ bf16_t f2bf(float f) { return (bf16_t)cvtpk(f, 0.f); }
; __device__ __forceinline__ v4i16_t lds_tr16(const bf16_t* p) { return __builtin_amdgcn_ds_read_tr16_b64_v4i16((LAS v4i16_t*)p); }
; __device__ void phase_attn(const Params& p, unsigned char* smem, int wave) {
;     ...
; #pragma unroll
;         for (int ks = 0; ks < 5; ++ks) {
;             u32x4 pu; pu.x = cvtpk(sc[2 * ks][0], sc[2 * ks][1]); pu.y = cvtpk(sc[2 * ks][2], sc[2 * ks][3]); pu.z = cvtpk(sc[2 * ks + 1][0], sc[2 * ks + 1][1]); pu.w = cvtpk(sc[2 * ks + 1][2], sc[2 * ks + 1][3]);
;             const bf16x8 pf = __builtin_bit_cast(bf16x8, pu);
;             const bf16_t* vrow = Vs + (16 * w4 + 32 * ks + 4 * gq + (ql >> 2)) * ATT_LD + 4 * (ql & 3);
; #pragma unroll
;             for (int et = 0; et < 4; ++et) {
;                 const v4i16_t t0 = lds_tr16(vrow + 16 * et);
;                 v4i16_t t1 = (v4i16_t){0, 0, 0, 0};
;                 if (ks < 4) t1 = lds_tr16(vrow + 16 * ATT_LD + 16 * et);
;                 const bf16x8 vf = __builtin_shufflevector(t0, t1, 0, 1, 2, 3, 4, 5, 6, 7);
;                 oacc[et] = __builtin_amdgcn_mfma_f32_16x16x32_bf16(pf, vf, oacc[et], 0, 0, 0); }
;             __builtin_amdgcn_sched_barrier(0);
;         }
; #pragma unroll
;         for (int j = 0; j < 4; ++j) { const float dq = __shfl(den, 4 * gq + j); const float inv = __builtin_amdgcn_rcpf(dq);
;             const int tok = gbase + (i0 + 16 * w4 + 4 * gq + j) * d + res;
; #pragma unroll
;             for (int et = 0; et < 4; ++et) ato[(size_t)tok * 512 + h * 64 + 16 * et + ql] = f2bf(oacc[et][j] * inv); }
;         if (gq == 0) { const int tok = gbase + qi * d + res; lse[((size_t)br * NTOK + tok) * 8 + h] = mx * 0.6931471805599453f + __logf(den); }
	v_mfma_f32_16x16x32_bf16 v[60:63], v[48:51], v[60:63], 0
	s_waitcnt lgkmcnt(1)
	v_mfma_f32_16x16x32_bf16 v[48:51], v[48:51], v[186:189], 0
	v_cvt_pk_bf16_f32 v186, v191, v192
	v_cvt_pk_bf16_f32 v187, v193, v196
	v_cvt_pk_bf16_f32 v188, v197, v198
	v_cvt_pk_bf16_f32 v189, v199, v200
	ds_read_b64_tr_b16 v[192:193], v179 offset:62208
	ds_read_b64_tr_b16 v[190:191], v179 offset:59904
	ds_read_b64_tr_b16 v[194:195], v179 offset:59936
	ds_read_b64_tr_b16 v[198:199], v179 offset:59968
	ds_read_b64_tr_b16 v[202:203], v179 offset:60000
	ds_read_b64_tr_b16 v[196:197], v179 offset:62240
	ds_read_b64_tr_b16 v[200:201], v179 offset:62272
	ds_read_b64_tr_b16 v[204:205], v179 offset:62304
	s_waitcnt lgkmcnt(6)
	v_mfma_f32_16x16x32_bf16 v[52:55], v[186:189], v[190:193], v[52:55]
	s_waitcnt lgkmcnt(2)
	v_mfma_f32_16x16x32_bf16 v[56:59], v[186:189], v[194:197], v[56:59]
	s_waitcnt lgkmcnt(1)
	v_mfma_f32_16x16x32_bf16 v[60:63], v[186:189], v[198:201], v[60:63]
	s_waitcnt lgkmcnt(0)
	v_mfma_f32_16x16x32_bf16 v[48:51], v[186:189], v[202:205], v[48:51]
	v_cvt_pk_bf16_f32 v186, v207, v208
	v_cvt_pk_bf16_f32 v187, v64, v65
	v_cvt_pk_bf16_f32 v188, v209, v210
	v_cvt_pk_bf16_f32 v189, v211, v212
	ds_read_b64_tr_b16 v[192:193], v180 offset:11520
	ds_read_b64_tr_b16 v[190:191], v179 offset:64512
	ds_read_b64_tr_b16 v[194:195], v179 offset:64544
	ds_read_b64_tr_b16 v[198:199], v179 offset:64576
	ds_read_b64_tr_b16 v[202:203], v179 offset:64608
	ds_read_b64_tr_b16 v[196:197], v180 offset:11552
	ds_read_b64_tr_b16 v[200:201], v180 offset:11584
	ds_read_b64_tr_b16 v[204:205], v180 offset:11616
	s_waitcnt lgkmcnt(6)
	v_mfma_f32_16x16x32_bf16 v[52:55], v[186:189], v[190:193], v[52:55]
	s_waitcnt lgkmcnt(2)
	v_mfma_f32_16x16x32_bf16 v[56:59], v[186:189], v[194:197], v[56:59]
	s_waitcnt lgkmcnt(1)
	v_mfma_f32_16x16x32_bf16 v[60:63], v[186:189], v[198:201], v[60:63]
	s_waitcnt lgkmcnt(0)
	v_mfma_f32_16x16x32_bf16 v[48:51], v[186:189], v[202:205], v[48:51]
	v_cvt_pk_bf16_f32 v186, v213, v214
	v_cvt_pk_bf16_f32 v187, v215, v216
	v_cvt_pk_bf16_f32 v188, v217, v218
	v_cvt_pk_bf16_f32 v189, v219, v220
	ds_read_b64_tr_b16 v[192:193], v180 offset:16128
	ds_read_b64_tr_b16 v[190:191], v180 offset:13824
	ds_read_b64_tr_b16 v[194:195], v180 offset:13856
	ds_read_b64_tr_b16 v[198:199], v180 offset:13888
	ds_read_b64_tr_b16 v[202:203], v180 offset:13920
	ds_read_b64_tr_b16 v[196:197], v180 offset:16160
	ds_read_b64_tr_b16 v[200:201], v180 offset:16192
	ds_read_b64_tr_b16 v[204:205], v180 offset:16224
	s_waitcnt lgkmcnt(6)
	v_mfma_f32_16x16x32_bf16 v[52:55], v[186:189], v[190:193], v[52:55]
	s_waitcnt lgkmcnt(2)
	v_mfma_f32_16x16x32_bf16 v[56:59], v[186:189], v[194:197], v[56:59]
	s_waitcnt lgkmcnt(1)
	v_mfma_f32_16x16x32_bf16 v[60:63], v[186:189], v[198:201], v[60:63]
	s_waitcnt lgkmcnt(0)
	v_mfma_f32_16x16x32_bf16 v[48:51], v[186:189], v[202:205], v[48:51]
	v_cvt_pk_bf16_f32 v12, v221, v222
	v_cvt_pk_bf16_f32 v13, v13, v14
	v_mov_b32_e32 v14, v15
	ds_read_b64_tr_b16 v[186:187], v180 offset:18432
	ds_read_b64_tr_b16 v[190:191], v180 offset:18464
	ds_read_b64_tr_b16 v[194:195], v180 offset:18496
	ds_read_b64_tr_b16 v[198:199], v180 offset:18528
	v_mov_b32_e32 v188, v15
	v_mov_b32_e32 v189, v15
	v_mov_b32_e32 v192, v15
	v_mov_b32_e32 v193, v15
	v_mov_b32_e32 v196, v15
	v_mov_b32_e32 v197, v15
	v_mov_b32_e32 v200, v15
	v_mov_b32_e32 v201, v15
	s_waitcnt lgkmcnt(3)
	v_mfma_f32_16x16x32_bf16 v[52:55], v[12:15], v[186:189], v[52:55]
	s_waitcnt lgkmcnt(2)
	v_mfma_f32_16x16x32_bf16 v[56:59], v[12:15], v[190:193], v[56:59]
	s_waitcnt lgkmcnt(1)
	v_mfma_f32_16x16x32_bf16 v[60:63], v[12:15], v[194:197], v[60:63]
	s_waitcnt lgkmcnt(0)
	v_mfma_f32_16x16x32_bf16 v[48:51], v[12:15], v[198:201], v[48:51]
	v_or_b32_e32 v14, v206, v141
	v_add_f32_e32 v12, v47, v223
	v_lshlrev_b32_e32 v14, 2, v14
	ds_bpermute_b32 v47, v14, v12
	s_add_i32 s62, s62, s61
	s_lshl_b32 s18, s57, 7
	s_add_u32 s18, s59, s18
	v_or_b32_e32 v13, v139, v141
	s_addc_u32 s19, s60, 0
	v_mov_b32_e32 v139, v15
	s_waitcnt lgkmcnt(0)
	v_rcp_f32_e32 v47, v47
	v_lshl_add_u64 v[64:65], s[18:19], 0, v[138:139]
	v_lshlrev_b32_e32 v139, s58, v13
	v_add_u32_e32 v186, s62, v139
	v_ashrrev_i32_e32 v187, 31, v186
	v_lshlrev_b64 v[186:187], 10, v[186:187]
	v_mul_f32_e32 v52, v52, v47
	v_lshl_add_u64 v[186:187], v[64:65], 0, v[186:187]
	v_cvt_pk_bf16_f32 v52, v52, s0
	global_store_short v[186:187], v52, off
	v_mul_f32_e32 v52, v56, v47
	ds_bpermute_b32 v56, v14, v12 offset:4
	v_cvt_pk_bf16_f32 v52, v52, s0
	global_store_short v[186:187], v52, off offset:32
	v_mul_f32_e32 v52, v60, v47
	v_mul_f32_e32 v47, v48, v47
	v_cvt_pk_bf16_f32 v47, v47, s0
	global_store_short v[186:187], v47, off offset:96
	s_waitcnt lgkmcnt(0)
	v_rcp_f32_e32 v47, v56
	v_or_b32_e32 v48, 1, v13
	v_cvt_pk_bf16_f32 v52, v52, s0
	v_lshlrev_b32_e32 v48, s58, v48
	global_store_short v[186:187], v52, off offset:64
	v_add_u32_e32 v186, s62, v48
	v_ashrrev_i32_e32 v187, 31, v186
	v_lshlrev_b64 v[186:187], 10, v[186:187]
	v_mul_f32_e32 v48, v53, v47
	v_lshl_add_u64 v[186:187], v[64:65], 0, v[186:187]
	v_cvt_pk_bf16_f32 v48, v48, s0
	ds_bpermute_b32 v52, v14, v12 offset:8
	global_store_short v[186:187], v48, off
	v_mul_f32_e32 v48, v57, v47
	v_cvt_pk_bf16_f32 v48, v48, s0
	global_store_short v[186:187], v48, off offset:32
	v_mul_f32_e32 v48, v61, v47
	v_mul_f32_e32 v47, v49, v47
	v_cvt_pk_bf16_f32 v48, v48, s0
	v_cvt_pk_bf16_f32 v47, v47, s0
	global_store_short v[186:187], v48, off offset:64
	global_store_short v[186:187], v47, off offset:96
	s_waitcnt lgkmcnt(0)
	v_rcp_f32_e32 v47, v52
	v_or_b32_e32 v48, 2, v13
	v_lshlrev_b32_e32 v48, s58, v48
	v_add_u32_e32 v48, s62, v48
	v_or_b32_e32 v14, 12, v14
	v_ashrrev_i32_e32 v49, 31, v48
	ds_bpermute_b32 v14, v14, v12
	v_lshlrev_b64 v[48:49], 10, v[48:49]
	v_mul_f32_e32 v52, v54, v47
	v_lshl_add_u64 v[48:49], v[64:65], 0, v[48:49]
	v_cvt_pk_bf16_f32 v52, v52, s0
	global_store_short v[48:49], v52, off
	v_mul_f32_e32 v52, v58, v47
	v_cvt_pk_bf16_f32 v52, v52, s0
	global_store_short v[48:49], v52, off offset:32
	v_mul_f32_e32 v52, v62, v47
	v_mul_f32_e32 v47, v50, v47
	s_waitcnt lgkmcnt(0)
	v_rcp_f32_e32 v14, v14
	v_or_b32_e32 v13, 3, v13
	v_cvt_pk_bf16_f32 v52, v52, s0
	v_cvt_pk_bf16_f32 v47, v47, s0
	v_lshlrev_b32_e32 v13, s58, v13
	global_store_short v[48:49], v52, off offset:64
	global_store_short v[48:49], v47, off offset:96
	v_add_u32_e32 v48, s62, v13
	v_ashrrev_i32_e32 v49, 31, v48
	v_lshlrev_b64 v[48:49], 10, v[48:49]
	v_mul_f32_e32 v13, v55, v14
	v_lshl_add_u64 v[48:49], v[64:65], 0, v[48:49]
	v_cvt_pk_bf16_f32 v13, v13, s0
	global_store_short v[48:49], v13, off
	v_mul_f32_e32 v13, v59, v14
	v_cvt_pk_bf16_f32 v13, v13, s0
	global_store_short v[48:49], v13, off offset:32
	v_mul_f32_e32 v13, v63, v14
	v_cvt_pk_bf16_f32 v13, v13, s0
	global_store_short v[48:49], v13, off offset:64
	v_mul_f32_e32 v13, v51, v14
	v_cvt_pk_bf16_f32 v13, v13, s0
	global_store_short v[48:49], v13, off offset:96
	s_and_saveexec_b64 s[20:21], s[0:1]
	s_cbranch_execz .LBB0_719
; __device__ void phase_attn(const Params& p, unsigned char* smem, int wave) {
;     ...
;         if (gq == 0) { const int tok = gbase + qi * d + res; lse[((size_t)br * NTOK + tok) * 8 + h] = mx * 0.6931471805599453f + __logf(den); }
	v_cmp_gt_f32_e32 vcc, s53, v12
	s_nop 1
	v_cndmask_b32_e64 v13, 0, 32, vcc
	v_ldexp_f32 v12, v12, v13
	v_log_f32_e32 v13, v12
	v_lshlrev_b32_e32 v12, s58, v45
	v_add_u32_e32 v12, s62, v12
	v_mul_f32_e32 v14, 0x3f317217, v13
	v_fma_f32 v14, v13, s54, -v14
	v_fmac_f32_e32 v14, 0x3377d1cf, v13
	v_fmac_f32_e32 v14, 0x3f317217, v13
	v_cmp_lt_f32_e64 s[18:19], |v13|, s55
	s_nop 1
	v_cndmask_b32_e64 v13, v13, v14, s[18:19]
	v_cndmask_b32_e32 v14, 0, v184, vcc
	v_sub_f32_e32 v14, v13, v14
	v_ashrrev_i32_e32 v13, 31, v12
	v_mad_i64_i32 v[12:13], s[18:19], s42, v185, v[12:13]
	v_lshlrev_b64 v[12:13], 5, v[12:13]
	v_lshl_add_u64 v[12:13], s[40:41], 0, v[12:13]
	s_lshl_b32 s42, s57, 2
	v_fmac_f32_e32 v14, 0x3f317218, v46
	v_lshl_add_u64 v[12:13], v[12:13], 0, s[42:43]
	global_store_dword v[12:13], v14, off
	s_branch .LBB0_719
